# final RMSNorm loop: g_final gains loaded once before the row loop, no vmcnt(0) between the four output stores
# baseline (speedup 1.0000x reference)
; DI float h_lo(unsigned u) { return (float)__builtin_bit_cast(h2_t, u)[0]; }
; DI float h_hi(unsigned u) { return (float)__builtin_bit_cast(h2_t, u)[1]; }
; DI int tid_opaque() { int t = threadIdx.x; asm volatile("" : "+v"(t)); return t; }
; #define G_XF (outp())
; __global__ void __launch_bounds__(512, 2) mega(Params p) {
;     ...
;   {
;     const int t2 = tid_opaque();
;     const int w = t2 >> 6, l = t2 & 63;
;     const float4* gf = (const float4*)inp(23);
;     for (int row = bid * 8 + w; row < NTOK; row += nb * 8) {
;       const uint2* xp = (const uint2*)(G_XB + (size_t)row * DM);
;       float4* op = (float4*)(G_XF + (size_t)row * DM);
;       float4 v[4];
;       float s2 = 0.f;
; #pragma unroll
;       for (int i = 0; i < 4; ++i) {
;         const uint2 u = xp[l + 64 * i];
;         v[i].x = h_lo(u.x); v[i].y = h_hi(u.x);
;         v[i].z = h_lo(u.y); v[i].w = h_hi(u.y);
;         s2 += v[i].x * v[i].x + v[i].y * v[i].y + v[i].z * v[i].z + v[i].w * v[i].w;
;       }
; #pragma unroll
;       for (int o = 32; o; o >>= 1) s2 += __shfl_xor(s2, o);
;       const float rr = rsqrtf(s2 * (1.f / 1024.f) + EPS);
; #pragma unroll
;       for (int i = 0; i < 4; ++i) {
;         const float4 g = gf[l + 64 * i];
;         float4 o4 = {v[i].x * rr * g.x, v[i].y * rr * g.y, v[i].z * rr * g.z, v[i].w * rr * g.w};
;         op[l + 64 * i] = o4;
;       }
;     }
.LBB0_1413:
	v_readlane_b32 s1, v252, 5
	v_ashrrev_i32_e32 v0, 6, v224
	s_mov_b32 s0, 23
	v_add_u32_e32 v0, s1, v0
	s_movk_i32 s1, 0x4000
	v_cmp_gt_i32_e32 vcc, s1, v0
	s_and_saveexec_b64 s[2:3], vcc
	s_cbranch_execz .LBB0_1416
	s_ashr_i32 s1, s0, 31
	s_lshl_b64 s[0:1], s[0:1], 3
	s_add_u32 s0, s70, s0
	s_addc_u32 s1, s71, s1
	s_load_dwordx2 s[2:3], s[0:1], 0x0
	v_readlane_b32 s0, v252, 1
	v_and_b32_e32 v6, 63, v224
	v_readlane_b32 s1, v252, 2
	v_ashrrev_i32_e32 v1, 31, v0
	v_lshlrev_b32_e32 v8, 4, v6
	s_lshl_b32 s0, s0, 3
	v_lshlrev_b64 v[4:5], 11, v[0:1]
	v_lshlrev_b32_e32 v6, 3, v6
	s_movk_i32 s1, 0x604
	v_mov_b32_e32 v9, 0
	v_or3_b32 v4, v4, v6, s1
	s_ashr_i32 s1, s0, 31
	v_lshlrev_b64 v[6:7], 12, v[0:1]
	s_movk_i32 s4, 0xc08
	v_and_b32_e32 v1, 64, v225
	s_waitcnt lgkmcnt(0)
	v_lshl_add_u64 v[2:3], s[2:3], 0, v[8:9]
	global_load_dwordx4 v[60:63], v[2:3], off
	global_load_dwordx4 v[64:67], v[2:3], off offset:1024
	global_load_dwordx4 v[68:71], v[2:3], off offset:2048
	global_load_dwordx4 v[72:75], v[2:3], off offset:3072
	s_lshl_b64 s[2:3], s[0:1], 11
	v_or3_b32 v6, v6, v8, s4
	s_lshl_b64 s[4:5], s[0:1], 12
	s_mov_b64 s[6:7], 0
	v_add_u32_e32 v1, 64, v1
	v_xor_b32_e32 v8, 32, v225
	v_xor_b32_e32 v9, 16, v225
	v_xor_b32_e32 v10, 8, v225
	v_xor_b32_e32 v11, 4, v225
	v_xor_b32_e32 v12, 2, v225
	v_xor_b32_e32 v13, 1, v225
	v_mov_b32_e32 v14, 0x358637bd
	s_mov_b32 s1, 0x800000
	s_movk_i32 s8, 0x3fff
.LBB0_1415:
	s_mov_b32 s10, 25
	s_ashr_i32 s11, s10, 31
	s_lshl_b64 s[10:11], s[10:11], 3
	s_add_u32 s10, s70, s10
	s_addc_u32 s11, s71, s11
	s_load_dwordx2 s[10:11], s[10:11], 0x0
	s_mov_b32 s12, 24
	v_cmp_lt_i32_e32 vcc, v8, v1
	s_ashr_i32 s13, s12, 31
	s_waitcnt lgkmcnt(0)
	v_lshl_add_u64 v[16:17], s[10:11], 0, v[4:5]
	global_load_dwordx2 v[20:21], v[16:17], off offset:-1540
	global_load_dwordx2 v[22:23], v[16:17], off offset:-1028
	global_load_dwordx2 v[24:25], v[16:17], off offset:-516
	global_load_dwordx2 v[26:27], v[16:17], off offset:-4
	v_cndmask_b32_e32 v15, v225, v8, vcc
	v_cmp_lt_i32_e32 vcc, v9, v1
	v_lshlrev_b32_e32 v15, 2, v15
	s_lshl_b64 s[10:11], s[12:13], 3
	v_cndmask_b32_e32 v16, v225, v9, vcc
	v_cmp_lt_i32_e32 vcc, v10, v1
	v_lshlrev_b32_e32 v54, 2, v16
	s_add_u32 s10, s70, s10
	v_cndmask_b32_e32 v17, v225, v10, vcc
	v_cmp_lt_i32_e32 vcc, v11, v1
	v_lshlrev_b32_e32 v55, 2, v17
	s_addc_u32 s11, s71, s11
	v_cndmask_b32_e32 v18, v225, v11, vcc
	v_cmp_lt_i32_e32 vcc, v12, v1
	v_lshlrev_b32_e32 v56, 2, v18
	s_load_dwordx2 s[10:11], s[10:11], 0x0
	v_cndmask_b32_e32 v19, v225, v12, vcc
	v_lshlrev_b32_e32 v57, 2, v19
	v_cmp_lt_i32_e32 vcc, v13, v1
	v_add_u32_e32 v0, s0, v0
	v_lshl_add_u64 v[4:5], v[4:5], 0, s[2:3]
	v_cndmask_b32_e32 v28, v225, v13, vcc
	v_lshlrev_b32_e32 v58, 2, v28
	s_waitcnt lgkmcnt(0)
	v_lshl_add_u64 v[28:29], s[10:11], 0, v[6:7]
	v_lshl_add_u64 v[6:7], v[6:7], 0, s[4:5]
	s_waitcnt vmcnt(3)
	v_cvt_f32_f16_sdwa v31, v20 dst_sel:DWORD dst_unused:UNUSED_PAD src0_sel:WORD_1
	s_waitcnt vmcnt(2)
	v_cvt_f32_f16_sdwa v33, v22 dst_sel:DWORD dst_unused:UNUSED_PAD src0_sel:WORD_1
	v_cvt_f32_f16_e32 v30, v20
	v_cvt_f32_f16_e32 v32, v22
	s_waitcnt vmcnt(1)
	v_cvt_f32_f16_sdwa v35, v24 dst_sel:DWORD dst_unused:UNUSED_PAD src0_sel:WORD_1
	s_waitcnt vmcnt(0)
	v_cvt_f32_f16_sdwa v37, v26 dst_sel:DWORD dst_unused:UNUSED_PAD src0_sel:WORD_1
	v_cvt_f32_f16_e32 v20, v21
	v_cvt_f32_f16_e32 v22, v23
	v_cvt_f32_f16_e32 v34, v24
	v_cvt_f32_f16_e32 v36, v26
	v_cvt_f32_f16_sdwa v21, v21 dst_sel:DWORD dst_unused:UNUSED_PAD src0_sel:WORD_1
	v_cvt_f32_f16_sdwa v23, v23 dst_sel:DWORD dst_unused:UNUSED_PAD src0_sel:WORD_1
	v_cvt_f32_f16_e32 v24, v25
	v_cvt_f32_f16_e32 v26, v27
	v_cvt_f32_f16_sdwa v25, v25 dst_sel:DWORD dst_unused:UNUSED_PAD src0_sel:WORD_1
	v_cvt_f32_f16_sdwa v27, v27 dst_sel:DWORD dst_unused:UNUSED_PAD src0_sel:WORD_1
	v_mov_b32_e32 v40, v31
	v_mov_b32_e32 v41, v33
	v_mov_b32_e32 v38, v30
	v_mov_b32_e32 v39, v32
	v_mov_b32_e32 v48, v35
	v_mov_b32_e32 v49, v37
	v_pk_mul_f32 v[40:41], v[40:41], v[40:41]
	v_mov_b32_e32 v42, v20
	v_mov_b32_e32 v43, v22
	v_mov_b32_e32 v46, v34
	v_mov_b32_e32 v47, v36
	v_pk_mul_f32 v[48:49], v[48:49], v[48:49]
	v_pk_fma_f32 v[38:39], v[38:39], v[38:39], v[40:41]
	v_mov_b32_e32 v44, v21
	v_mov_b32_e32 v45, v23
	v_mov_b32_e32 v50, v24
	v_mov_b32_e32 v51, v26
	v_pk_fma_f32 v[40:41], v[46:47], v[46:47], v[48:49]
	v_pk_fma_f32 v[38:39], v[42:43], v[42:43], v[38:39]
	v_mov_b32_e32 v52, v25
	v_mov_b32_e32 v53, v27
	v_pk_fma_f32 v[40:41], v[50:51], v[50:51], v[40:41]
	v_pk_fma_f32 v[38:39], v[44:45], v[44:45], v[38:39]
	v_pk_fma_f32 v[40:41], v[52:53], v[52:53], v[40:41]
	v_add_f32_e32 v38, v38, v39
	v_add_f32_e32 v38, v38, v40
	v_add_f32_e32 v38, v38, v41
	ds_bpermute_b32 v15, v15, v38
	s_waitcnt lgkmcnt(0)
	v_add_f32_e32 v15, v38, v15
	ds_bpermute_b32 v38, v54, v15
	s_waitcnt lgkmcnt(0)
	v_add_f32_e32 v15, v15, v38
	ds_bpermute_b32 v38, v55, v15
	s_waitcnt lgkmcnt(0)
	v_add_f32_e32 v15, v15, v38
	ds_bpermute_b32 v38, v56, v15
	s_waitcnt lgkmcnt(0)
	v_add_f32_e32 v15, v15, v38
	ds_bpermute_b32 v38, v57, v15
	s_waitcnt lgkmcnt(0)
	v_add_f32_e32 v15, v15, v38
	ds_bpermute_b32 v38, v58, v15
	s_waitcnt lgkmcnt(0)
	v_add_f32_e32 v15, v15, v38
	v_fmamk_f32 v15, v15, 0x3a800000, v14
	v_mul_f32_e32 v38, 0x4b800000, v15
	v_cmp_gt_f32_e32 vcc, s1, v15
	s_nop 1
	v_cndmask_b32_e32 v15, v15, v38, vcc
	v_rsq_f32_e32 v15, v15
	s_nop 0
	v_mul_f32_e32 v38, 0x45800000, v15
	v_cndmask_b32_e32 v38, v15, v38, vcc
	v_pk_mul_f32 v[30:31], v[38:39], v[30:31] op_sel_hi:[0,1]
	v_pk_mul_f32 v[20:21], v[38:39], v[20:21] op_sel_hi:[0,1]
	v_pk_mul_f32 v[16:17], v[60:61], v[30:31]
	v_pk_mul_f32 v[18:19], v[62:63], v[20:21]
	global_store_dwordx4 v[28:29], v[16:19], off offset:-3080
	v_pk_mul_f32 v[20:21], v[38:39], v[32:33] op_sel_hi:[0,1]
	v_pk_mul_f32 v[22:23], v[38:39], v[22:23] op_sel_hi:[0,1]
	v_cmp_lt_i32_e32 vcc, s8, v0
	s_or_b64 s[6:7], vcc, s[6:7]
	v_pk_mul_f32 v[76:77], v[64:65], v[20:21]
	v_pk_mul_f32 v[78:79], v[66:67], v[22:23]
	global_store_dwordx4 v[28:29], v[76:79], off offset:-2056
	v_pk_mul_f32 v[20:21], v[38:39], v[34:35] op_sel_hi:[0,1]
	v_pk_mul_f32 v[22:23], v[38:39], v[24:25] op_sel_hi:[0,1]
	v_pk_mul_f32 v[80:81], v[68:69], v[20:21]
	v_pk_mul_f32 v[82:83], v[70:71], v[22:23]
	global_store_dwordx4 v[28:29], v[80:83], off offset:-1032
	v_pk_mul_f32 v[20:21], v[38:39], v[36:37] op_sel_hi:[0,1]
	v_pk_mul_f32 v[22:23], v[38:39], v[26:27] op_sel_hi:[0,1]
	v_pk_mul_f32 v[84:85], v[72:73], v[20:21]
	v_pk_mul_f32 v[86:87], v[74:75], v[22:23]
	global_store_dwordx4 v[28:29], v[84:87], off offset:-8
	s_andn2_b64 exec, exec, s[6:7]
	s_cbranch_execnz .LBB0_1415
